# barrier between phase 0 and normmod1(l=0) replaced by a counter on the 32 modulation GEMV items it needs (MOD written through)
# speedup vs baseline: 1.0153x; 1.0079x over previous
.LBB0_8:
	v_writelane_b32 v254, s78, 24
	s_mov_b32 s0, s49
	s_ashr_i32 s1, s0, 31
	v_writelane_b32 v254, s79, 25
	v_writelane_b32 v254, s76, 26
	v_readlane_b32 s2, v253, 3
	v_readlane_b32 s3, v253, 4
	v_writelane_b32 v254, s77, 27
	v_writelane_b32 v254, s74, 28
	s_add_u32 s0, s2, s0
	s_addc_u32 s1, s3, s1
	v_writelane_b32 v254, s75, 29
	v_writelane_b32 v254, s66, 30
	v_readlane_b32 s24, v253, 62
	v_writelane_b32 v254, s67, 31
	v_readlane_b32 s25, v253, 63
	s_load_dwordx16 s[52:67], s[0:1], 0x0
	s_load_dwordx2 s[30:31], s[0:1], 0x70
	s_load_dwordx4 s[36:39], s[0:1], 0x60
	s_load_dwordx8 s[12:19], s[0:1], 0x40
	s_load_dwordx2 s[2:3], s[0:1], 0x88
	s_load_dwordx8 s[68:75], s[0:1], 0x98
	s_load_dwordx16 s[80:95], s[0:1], 0xc0
	s_load_dwordx4 s[96:99], s[0:1], 0x120
	s_load_dwordx8 s[4:11], s[0:1], 0x100
	s_waitcnt lgkmcnt(0)
	s_movk_i32 s100, 0
	s_cmp_eq_u32 s46, 6
	s_cselect_b32 s100, 8, s100
	s_cmp_eq_u32 s46, 10
	s_cselect_b32 s100, 16, s100
	s_cmp_eq_u32 s46, 15
	s_cselect_b32 s100, 24, s100
	s_cmp_eq_u32 s46, 19
	s_cselect_b32 s100, 32, s100
	s_cmp_eq_u32 s46, 1
	s_cselect_b32 s100, 32, s100
	s_cmp_eq_u32 s100, 0
	s_cbranch_scc1 .Lpf_done
	v_lshrrev_b32_e32 v2, 6, v1
	s_nop 1
	v_readfirstlane_b32 s0, v2
	s_cmp_lg_u32 s0, 0
	s_cbranch_scc1 .Lpf_wait
	v_readlane_b32 s0, v253, 0
	s_lshr_b32 s1, s0, 4
	s_mov_b32 vcc_lo, 15
	s_mov_b32 vcc_hi, 0
	s_cmp_eq_u32 s46, 19
	s_cbranch_scc0 .Lpf_t1
	s_lshr_b32 s1, s0, 5
	s_mov_b32 vcc_lo, 7
.Lpf_t1:
	s_cmp_eq_u32 s46, 1
	s_cbranch_scc0 .Lpf_t3
	s_mov_b32 s1, 0
	s_mov_b32 vcc_lo, 31
	s_movk_i32 vcc_hi, 0x1c0

.LBB0_722:
	global_load_dword v7, v[2:3], off
	v_ashrrev_i32_e32 v8, 6, v66
	v_add_u32_e32 v9, 0x200, v66
	s_movk_i32 s8, 0xff3f
	v_lshl_add_u32 v38, v8, 8, v6
	v_cmp_lt_i32_e32 vcc, s8, v66
	v_add_u32_e32 v40, s15, v8
	v_mov_b32_e32 v66, v9
	ds_read2st64_b32 v[8:9], v38 offset0:80 offset1:85
	ds_read2st64_b32 v[10:11], v38 offset0:90 offset1:95
	ds_read2st64_b32 v[12:13], v38 offset0:100 offset1:105
	ds_read2st64_b32 v[14:15], v38 offset0:110 offset1:115
	ds_read2st64_b32 v[16:17], v38 offset0:120 offset1:125
	ds_read2st64_b32 v[18:19], v38 offset0:130 offset1:135
	ds_read2st64_b32 v[20:21], v38 offset0:140 offset1:145
	ds_read2st64_b32 v[22:23], v38 offset0:150 offset1:155
	ds_read2st64_b32 v[24:25], v38 offset0:160 offset1:165
	ds_read2st64_b32 v[26:27], v38 offset0:170 offset1:175
	ds_read2st64_b32 v[28:29], v38 offset0:180 offset1:185
	ds_read2st64_b32 v[30:31], v38 offset0:190 offset1:195
	ds_read2st64_b32 v[32:33], v38 offset0:200 offset1:205
	ds_read2st64_b32 v[34:35], v38 offset0:210 offset1:215
	ds_read2st64_b32 v[36:37], v38 offset0:220 offset1:225
	ds_read2st64_b32 v[38:39], v38 offset0:230 offset1:235
	s_or_b64 s[6:7], vcc, s[6:7]
	v_mad_i64_i32 v[40:41], s[8:9], v40, s29, v[4:5]
	s_waitcnt vmcnt(0) lgkmcnt(14)
	v_add_f32_e32 v7, v7, v8
	v_add_f32_e32 v7, v7, v9
	v_add_f32_e32 v7, v7, v10
	v_add_f32_e32 v7, v7, v11
	s_waitcnt lgkmcnt(13)
	v_add_f32_e32 v7, v7, v12
	v_add_f32_e32 v7, v7, v13
	s_waitcnt lgkmcnt(12)
	v_add_f32_e32 v7, v7, v14
	v_add_f32_e32 v7, v7, v15
	s_waitcnt lgkmcnt(11)
	v_add_f32_e32 v7, v7, v16
	v_add_f32_e32 v7, v7, v17
	s_waitcnt lgkmcnt(10)
	v_add_f32_e32 v7, v7, v18
	v_add_f32_e32 v7, v7, v19
	s_waitcnt lgkmcnt(9)
	v_add_f32_e32 v7, v7, v20
	v_add_f32_e32 v7, v7, v21
	s_waitcnt lgkmcnt(8)
	v_add_f32_e32 v7, v7, v22
	v_add_f32_e32 v7, v7, v23
	s_waitcnt lgkmcnt(7)
	v_add_f32_e32 v7, v7, v24
	v_add_f32_e32 v7, v7, v25
	s_waitcnt lgkmcnt(6)
	v_add_f32_e32 v7, v7, v26
	v_add_f32_e32 v7, v7, v27
	s_waitcnt lgkmcnt(5)
	v_add_f32_e32 v7, v7, v28
	v_add_f32_e32 v7, v7, v29
	s_waitcnt lgkmcnt(4)
	v_add_f32_e32 v7, v7, v30
	v_add_f32_e32 v7, v7, v31
	s_waitcnt lgkmcnt(3)
	v_add_f32_e32 v7, v7, v32
	v_add_f32_e32 v7, v7, v33
	s_waitcnt lgkmcnt(2)
	v_add_f32_e32 v7, v7, v34
	v_add_f32_e32 v7, v7, v35
	s_waitcnt lgkmcnt(1)
	v_add_f32_e32 v7, v7, v36
	v_add_f32_e32 v7, v7, v37
	s_waitcnt lgkmcnt(0)
	v_add_f32_e32 v7, v7, v38
	v_add_f32_e32 v7, v7, v39
	global_store_dword v[40:41], v7, off sc1
	s_andn2_b64 exec, exec, s[6:7]
	s_cbranch_execnz .LBB0_722
.LBB0_723:
	s_or_b64 exec, exec, s[10:11]
	s_waitcnt vmcnt(0)
	s_barrier
	s_cmpk_gt_u32 s12, 31
	s_cbranch_scc1 .Lpf0_norel
	v_lshrrev_b32_e32 v2, 6, v1
	s_nop 1
	v_readfirstlane_b32 s6, v2
	s_cmp_lg_u32 s6, 0
	s_cbranch_scc1 .Lpf0_norel
	v_readlane_b32 s8, v253, 5
	v_readlane_b32 s9, v253, 6
	v_mov_b32_e32 v2, 0x1c0
	v_mov_b32_e32 v3, 1
	s_nop 3
	s_mov_b64 exec, 1
	global_atomic_add v2, v3, s[8:9]
	s_mov_b64 exec, -1
.Lpf0_norel:
	s_mov_b64 s[6:7], -1

.LBB0_727:
	s_mov_b64 s[2:3], s[46:47]
	s_add_i32 s18, s2, 1
	s_cmp_ge_i32 s18, s3
	v_readlane_b32 s30, v254, 6
	v_readlane_b32 s38, v254, 8
	v_readlane_b32 s56, v254, 22
	v_readlane_b32 s31, v254, 7
	v_readlane_b32 s39, v254, 9
	v_readlane_b32 s57, v254, 23
	s_cbranch_scc1 .LBB0_781
	s_cmp_eq_u32 s2, 5
	s_cbranch_scc1 .LBB0_781
	s_cmp_eq_u32 s2, 14
	s_cbranch_scc1 .LBB0_781
	s_cmp_eq_u32 s2, 9
	s_cbranch_scc1 .LBB0_781
	s_cmp_eq_u32 s2, 18
	s_cbranch_scc1 .LBB0_781
	s_cmp_eq_u32 s2, 4
	s_cbranch_scc1 .LBB0_781
	s_cmp_eq_u32 s2, 13
	s_cbranch_scc1 .LBB0_781
	s_cmp_eq_u32 s2, 0
	s_cbranch_scc1 .LBB0_781
	s_waitcnt vmcnt(0)
	s_waitcnt lgkmcnt(0)
	s_barrier
	s_mov_b64 s[2:3], exec
	v_readlane_b32 s4, v253, 7
	v_readlane_b32 s5, v253, 8
	s_and_b64 s[4:5], s[2:3], s[4:5]
	s_mov_b64 exec, s[4:5]
	s_cbranch_execz .LBB0_780
	s_add_i32 s13, 0, 0x24000
	s_mov_b64 s[4:5], src_shared_base
	s_cmp_lg_u32 s13, -1
	s_cselect_b32 s4, s13, 0
	s_cselect_b32 s6, s5, 0
	s_add_i32 s12, 0, 0x24004
	s_cmp_lg_u32 s12, -1
	v_mov_b32_e32 v2, s4
	v_mov_b32_e32 v3, s6
	s_cselect_b32 s4, s12, 0
	s_cselect_b32 s5, s5, 0
	s_waitcnt vmcnt(0) expcnt(0) lgkmcnt(0)
	s_and_b32 s4, s101, 0xffff
	v_mov_b32_e32 v4, s4
	v_mov_b32_e32 v2, s4
	v_mov_b32_e32 v3, s5
	s_lshr_b32 s4, s101, 16
	v_mov_b32_e32 v2, s4
	s_waitcnt vmcnt(0) lgkmcnt(0)
	v_cmp_eq_u32_e32 vcc, 0, v4
	s_and_saveexec_b64 s[4:5], vcc
	s_cbranch_execz .LBB0_744
	s_mov_b32 s14, 1
	s_branch .LBB0_732
